# c16 + accumulators zeroed with v_mov_b64 + sample-row gnorm/scale/shift loads issued before the block-reduction barriers (norm phases)
# speedup vs baseline: 1.0041x; 1.0041x over previous
.LBB0_253:
	s_or_b64 exec, exec, s[8:9]
	s_add_i32 s9, s12, 4
	s_add_i32 s8, s12, 0x2000
	s_mul_hi_i32 s13, s9, 0x12000
	s_mul_i32 s9, s9, 0x12000
	s_add_u32 s14, s23, s9
	s_addc_u32 s15, s30, s13
	v_lshl_add_u64 v[34:35], s[14:15], 0, v[6:7]
	v_add_co_u32_e32 v42, vcc, s3, v34
	global_load_dwordx4 v[30:33], v[8:9], off
	v_addc_co_u32_e32 v43, vcc, 0, v35, vcc
	global_load_dwordx4 v[34:37], v[42:43], off
	global_load_dwordx4 v[38:41], v6, s[14:15]
	s_waitcnt lgkmcnt(0)
	s_waitcnt lgkmcnt(0)
	s_barrier
	ds_read_b128 v[22:25], v7
	ds_read_b128 v[26:29], v7 offset:16
	s_waitcnt lgkmcnt(0)
	s_waitcnt lgkmcnt(0)
	s_barrier
	v_add_f32_e32 v21, 0, v22
	v_add_f32_e32 v21, v21, v23
	v_add_f32_e32 v21, v21, v24
	v_add_f32_e32 v21, v21, v25
	v_add_f32_e32 v21, v21, v26
	v_add_f32_e32 v21, v21, v27
	v_add_f32_e32 v21, v21, v28
	v_add_f32_e32 v21, v21, v29
	v_fmamk_f32 v21, v21, 0x3a000000, v19
	v_mul_f32_e32 v22, 0x4f800000, v21
	v_cmp_gt_f32_e32 vcc, s11, v21
	s_ashr_i32 s9, s8, 31
	s_lshl_b64 s[8:9], s[8:9], 12
	v_cndmask_b32_e32 v21, v21, v22, vcc
	v_sqrt_f32_e32 v24, v21
	v_lshl_add_u64 v[22:23], v[10:11], 0, s[8:9]
	s_add_i32 s12, s12, s20
	s_cmpk_lt_i32 s12, 0x80
	v_add_u32_e32 v25, -1, v24
	v_add_u32_e32 v26, 1, v24
	v_fma_f32 v27, -v25, v24, v21
	v_fma_f32 v28, -v26, v24, v21
	v_cmp_ge_f32_e64 s[8:9], 0, v27
	v_lshl_add_u64 v[12:13], v[12:13], 0, s[4:5]
	s_nop 0
	v_cndmask_b32_e64 v24, v24, v25, s[8:9]
	v_cmp_lt_f32_e64 s[8:9], 0, v28
	s_nop 1
	v_cndmask_b32_e64 v24, v24, v26, s[8:9]
	v_mul_f32_e32 v25, 0x37800000, v24
	v_cndmask_b32_e32 v24, v24, v25, vcc
	v_cmp_class_f32_e32 vcc, v21, v20
	s_nop 1
	v_cndmask_b32_e32 v21, v24, v21, vcc
	v_div_scale_f32 v24, s[8:9], v21, v21, 1.0
	v_rcp_f32_e32 v25, v24
	v_div_scale_f32 v26, vcc, 1.0, v21, 1.0
	v_fma_f32 v27, -v24, v25, 1.0
	v_fmac_f32_e32 v25, v27, v25
	v_mul_f32_e32 v27, v26, v25
	v_fma_f32 v28, -v24, v27, v26
	v_fmac_f32_e32 v27, v28, v25
	v_fma_f32 v24, -v24, v27, v26
	v_div_fmas_f32 v24, v24, v25, v27
	v_div_fixup_f32 v24, v24, v21, 1.0
	v_pk_mul_f32 v[4:5], v[4:5], v[24:25] op_sel_hi:[1,0]
	v_pk_mul_f32 v[2:3], v[2:3], v[24:25] op_sel_hi:[1,0]
	s_waitcnt vmcnt(2)
	v_pk_mul_f32 v[4:5], v[32:33], v[4:5]
	v_pk_mul_f32 v[2:3], v[30:31], v[2:3]
	s_waitcnt vmcnt(1)
	v_pk_add_f32 v[24:25], v[36:37], 1.0 op_sel_hi:[1,0]
	v_pk_add_f32 v[26:27], v[34:35], 1.0 op_sel_hi:[1,0]
	s_waitcnt vmcnt(0)
	v_pk_fma_f32 v[4:5], v[24:25], v[4:5], v[40:41]
	v_pk_fma_f32 v[2:3], v[26:27], v[2:3], v[38:39]
	s_nop 0
	v_cvt_pk_bf16_f32 v2, v2, v3
	v_cvt_pk_bf16_f32 v3, v4, v5
	global_store_dwordx2 v[22:23], v[2:3], off
	s_cbranch_scc0 .LBB0_256

.LBB0_504:
	s_or_b64 exec, exec, s[14:15]
	s_add_u32 s14, s17, s28
	s_addc_u32 s15, s18, s25
	v_lshl_add_u64 v[36:37], s[14:15], 0, v[2:3]
	v_add_co_u32_e32 v36, vcc, s3, v36
	global_load_dwordx4 v[32:35], v[6:7], off
	v_addc_co_u32_e32 v37, vcc, 0, v37, vcc
	global_load_dwordx4 v[36:39], v[36:37], off
	s_nop 0
	global_load_dwordx4 v[40:43], v2, s[14:15]
	s_waitcnt lgkmcnt(0)
	s_waitcnt lgkmcnt(0)
	s_barrier
	ds_read_b128 v[24:27], v3
	ds_read_b128 v[28:31], v3 offset:16
	s_waitcnt lgkmcnt(0)
	s_waitcnt lgkmcnt(0)
	s_barrier
	v_add_f32_e32 v23, 0, v24
	v_add_f32_e32 v23, v23, v25
	v_add_f32_e32 v23, v23, v26
	v_add_f32_e32 v23, v23, v27
	v_add_f32_e32 v23, v23, v28
	v_add_f32_e32 v23, v23, v29
	v_add_f32_e32 v23, v23, v30
	v_add_f32_e32 v23, v23, v31
	v_fmamk_f32 v23, v23, 0x3a000000, v21
	v_mul_f32_e32 v24, 0x4f800000, v23
	v_cmp_gt_f32_e32 vcc, s21, v23
	v_lshl_add_u64 v[44:45], v[8:9], 0, s[8:9]
	s_add_i32 s24, s24, s20
	v_cndmask_b32_e32 v23, v23, v24, vcc
	v_sqrt_f32_e32 v24, v23
	s_add_u32 s4, s4, s10
	s_addc_u32 s5, s5, s11
	s_add_u32 s12, s12, s10
	v_add_u32_e32 v25, -1, v24
	v_add_u32_e32 v26, 1, v24
	v_fma_f32 v27, -v25, v24, v23
	v_fma_f32 v28, -v26, v24, v23
	v_cmp_ge_f32_e64 s[8:9], 0, v27
	s_addc_u32 s13, s13, s11
	s_cmpk_lt_i32 s24, 0x80
	v_cndmask_b32_e64 v24, v24, v25, s[8:9]
	v_cmp_lt_f32_e64 s[8:9], 0, v28
	s_nop 1
	v_cndmask_b32_e64 v24, v24, v26, s[8:9]
	v_mul_f32_e32 v25, 0x37800000, v24
	v_cndmask_b32_e32 v24, v24, v25, vcc
	v_cmp_class_f32_e32 vcc, v23, v22
	s_nop 1
	v_cndmask_b32_e32 v23, v24, v23, vcc
	v_div_scale_f32 v24, s[8:9], v23, v23, 1.0
	v_rcp_f32_e32 v25, v24
	v_div_scale_f32 v26, vcc, 1.0, v23, 1.0
	v_fma_f32 v27, -v24, v25, 1.0
	v_fmac_f32_e32 v25, v27, v25
	v_mul_f32_e32 v27, v26, v25
	v_fma_f32 v28, -v24, v27, v26
	v_fmac_f32_e32 v27, v28, v25
	v_fma_f32 v24, -v24, v27, v26
	v_div_fmas_f32 v24, v24, v25, v27
	v_div_fixup_f32 v24, v24, v23, 1.0
	v_pk_mul_f32 v[14:15], v[24:25], v[14:15] op_sel_hi:[0,1]
	v_pk_mul_f32 v[12:13], v[24:25], v[12:13] op_sel_hi:[0,1]
	s_waitcnt vmcnt(2)
	v_pk_mul_f32 v[12:13], v[32:33], v[12:13]
	v_pk_mul_f32 v[14:15], v[34:35], v[14:15]
	s_waitcnt vmcnt(1)
	v_pk_add_f32 v[24:25], v[38:39], 1.0 op_sel_hi:[1,0]
	v_pk_add_f32 v[26:27], v[36:37], 1.0 op_sel_hi:[1,0]
	s_waitcnt vmcnt(0)
	v_pk_fma_f32 v[14:15], v[24:25], v[14:15], v[42:43]
	v_pk_fma_f32 v[12:13], v[26:27], v[12:13], v[40:41]
	s_nop 0
	v_cvt_pk_bf16_f32 v12, v12, v13
	v_cvt_pk_bf16_f32 v13, v14, v15
	global_store_dwordx2 v[44:45], v[12:13], off
	s_cbranch_scc0 .LBB0_507

.LBB0_1075:
	s_or_b64 exec, exec, s[10:11]
	s_add_u32 s10, s13, s19
	s_addc_u32 s11, s14, s18
	v_lshl_add_u64 v[36:37], s[10:11], 0, v[2:3]
	v_add_co_u32_e32 v44, vcc, s3, v36
	global_load_dwordx4 v[32:35], v[4:5], off
	v_addc_co_u32_e32 v45, vcc, 0, v37, vcc
	global_load_dwordx4 v[36:39], v[44:45], off
	global_load_dwordx4 v[40:43], v2, s[10:11]
	s_waitcnt lgkmcnt(0)
	s_waitcnt lgkmcnt(0)
	s_barrier
	ds_read_b128 v[24:27], v3
	ds_read_b128 v[28:31], v3 offset:16
	s_waitcnt lgkmcnt(0)
	s_waitcnt lgkmcnt(0)
	s_barrier
	v_add_f32_e32 v23, 0, v24
	v_add_f32_e32 v23, v23, v25
	v_add_f32_e32 v23, v23, v26
	v_add_f32_e32 v23, v23, v27
	v_add_f32_e32 v23, v23, v28
	v_add_f32_e32 v23, v23, v29
	v_add_f32_e32 v23, v23, v30
	v_add_f32_e32 v23, v23, v31
	v_fmamk_f32 v23, v23, 0x3a000000, v21
	v_mul_f32_e32 v24, 0x4f800000, v23
	v_cmp_gt_f32_e32 vcc, s16, v23
	s_add_i32 s17, s17, s20
	s_cmpk_lt_i32 s17, 0x80
	v_cndmask_b32_e32 v23, v23, v24, vcc
	v_sqrt_f32_e32 v26, v23
	v_lshl_add_u64 v[24:25], v[6:7], 0, s[8:9]
	v_lshl_add_u64 v[10:11], v[10:11], 0, s[4:5]
	v_add_u32_e32 v27, -1, v26
	v_add_u32_e32 v28, 1, v26
	v_fma_f32 v29, -v27, v26, v23
	v_fma_f32 v30, -v28, v26, v23
	v_cmp_ge_f32_e64 s[8:9], 0, v29
	s_nop 1
	v_cndmask_b32_e64 v26, v26, v27, s[8:9]
	v_cmp_lt_f32_e64 s[8:9], 0, v30
	s_nop 1
	v_cndmask_b32_e64 v26, v26, v28, s[8:9]
	v_mul_f32_e32 v27, 0x37800000, v26
	v_cndmask_b32_e32 v26, v26, v27, vcc
	v_cmp_class_f32_e32 vcc, v23, v22
	s_nop 1
	v_cndmask_b32_e32 v23, v26, v23, vcc
	v_div_scale_f32 v26, s[8:9], v23, v23, 1.0
	v_rcp_f32_e32 v27, v26
	v_div_scale_f32 v28, vcc, 1.0, v23, 1.0
	v_fma_f32 v29, -v26, v27, 1.0
	v_fmac_f32_e32 v27, v29, v27
	v_mul_f32_e32 v29, v28, v27
	v_fma_f32 v30, -v26, v29, v28
	v_fmac_f32_e32 v29, v30, v27
	v_fma_f32 v26, -v26, v29, v28
	v_div_fmas_f32 v26, v26, v27, v29
	v_div_fixup_f32 v26, v26, v23, 1.0
	v_pk_mul_f32 v[14:15], v[26:27], v[14:15] op_sel_hi:[0,1]
	v_pk_mul_f32 v[12:13], v[26:27], v[12:13] op_sel_hi:[0,1]
	s_waitcnt vmcnt(2)
	v_pk_mul_f32 v[12:13], v[32:33], v[12:13]
	v_pk_mul_f32 v[14:15], v[34:35], v[14:15]
	s_waitcnt vmcnt(1)
	v_pk_add_f32 v[26:27], v[38:39], 1.0 op_sel_hi:[1,0]
	v_pk_add_f32 v[28:29], v[36:37], 1.0 op_sel_hi:[1,0]
	s_waitcnt vmcnt(0)
	v_pk_fma_f32 v[14:15], v[26:27], v[14:15], v[42:43]
	v_pk_fma_f32 v[12:13], v[28:29], v[12:13], v[40:41]
	s_nop 0
	v_cvt_pk_bf16_f32 v12, v12, v13
	v_cvt_pk_bf16_f32 v13, v14, v15
	global_store_dwordx2 v[24:25], v[12:13], off
	s_cbranch_scc0 .LBB0_1078

.LBB0_1328:
	s_or_b64 exec, exec, s[0:1]
	global_load_dwordx4 v[30:33], v[14:15], off
	s_waitcnt lgkmcnt(0)
	s_waitcnt lgkmcnt(0)
	s_barrier
	ds_read_b128 v[4:7], v13
	ds_read_b128 v[8:11], v13 offset:16
	s_waitcnt lgkmcnt(0)
	s_waitcnt lgkmcnt(0)
	s_barrier
	v_add_f32_e32 v4, 0, v4
	v_add_f32_e32 v4, v4, v5
	v_add_f32_e32 v4, v4, v6
	v_add_f32_e32 v4, v4, v7
	v_add_f32_e32 v4, v4, v8
	v_add_f32_e32 v4, v4, v9
	v_add_f32_e32 v4, v4, v10
	v_add_f32_e32 v4, v4, v11
	v_fmamk_f32 v4, v4, 0x3a000000, v28
	v_mul_f32_e32 v5, 0x4f800000, v4
	v_cmp_gt_f32_e32 vcc, s13, v4
	s_lshl_b64 s[0:1], s[8:9], 13
	s_add_i32 s2, s2, s20
	v_cndmask_b32_e32 v6, v4, v5, vcc
	v_sqrt_f32_e32 v7, v6
	v_lshl_add_u64 v[4:5], v[18:19], 0, s[0:1]
	s_cmpk_lt_i32 s2, 0x80
	v_lshl_add_u64 v[20:21], v[20:21], 0, s[6:7]
	v_add_u32_e32 v8, -1, v7
	v_add_u32_e32 v9, 1, v7
	v_fma_f32 v10, -v8, v7, v6
	v_fma_f32 v11, -v9, v7, v6
	v_cmp_ge_f32_e64 s[0:1], 0, v10
	s_nop 1
	v_cndmask_b32_e64 v7, v7, v8, s[0:1]
	v_cmp_lt_f32_e64 s[0:1], 0, v11
	s_nop 1
	v_cndmask_b32_e64 v7, v7, v9, s[0:1]
	v_mul_f32_e32 v8, 0x37800000, v7
	v_cndmask_b32_e32 v7, v7, v8, vcc
	v_cmp_class_f32_e32 vcc, v6, v29
	s_nop 1
	v_cndmask_b32_e32 v6, v7, v6, vcc
	v_div_scale_f32 v7, s[0:1], v6, v6, 1.0
	v_rcp_f32_e32 v8, v7
	v_div_scale_f32 v9, vcc, 1.0, v6, 1.0
	v_fma_f32 v10, -v7, v8, 1.0
	v_fmac_f32_e32 v8, v10, v8
	v_mul_f32_e32 v10, v9, v8
	v_fma_f32 v11, -v7, v10, v9
	v_fmac_f32_e32 v10, v11, v8
	v_fma_f32 v7, -v7, v10, v9
	v_div_fmas_f32 v7, v7, v8, v10
	v_div_fixup_f32 v6, v7, v6, 1.0
	v_pk_mul_f32 v[0:1], v[6:7], v[0:1] op_sel_hi:[0,1]
	v_pk_mul_f32 v[2:3], v[6:7], v[2:3] op_sel_hi:[0,1]
	s_waitcnt vmcnt(0)
	v_pk_mul_f32 v[2:3], v[32:33], v[2:3]
	v_pk_mul_f32 v[0:1], v[30:31], v[0:1]
	global_store_dwordx4 v[4:5], v[0:3], off nt
	s_cbranch_scc0 .LBB0_1331
